# SSD chunk loop: dt-load wait moved to its consumer (counted vmcnt), epilogue z waits counted per path instead of draining the next-chunk prefetch
# speedup vs baseline: 1.5212x; 1.0045x over previous
; #define S2_ISSUE_Z(T0) do { _Pragma("unroll") for (int ig = 0; ig < 4; ++ig) zr[ig] = *(const u32x2*)(pbase + (size_t)((T0) + 32 * lt + l32o) * LDP + C_Z + hd * 64 + 32 * ph + 8 * ig + 4 * hho); } while (0)
; DI void ssd_pair_item(const Params& P, unsigned char* smem, int b, int hp) {
;     ...
;     { S2_ROLES(tid0) S2_ISSUE(0); S2_ISSUE_Z(0); }
.LBB0_294:
	s_or_b64 exec, exec, s[72:73]
	v_mul_u32_u24_e32 v64, 0x7600, v2
	v_lshl_add_u64 v[2:3], s[70:71], 0, v[64:65]
	v_lshl_add_u64 v[0:1], v[0:1], 1, v[2:3]
	v_add_co_u32_e32 v2, vcc, 0x1000, v0
	v_mov_b32_e32 v191, 0
	s_nop 0
	v_addc_co_u32_e32 v3, vcc, 0, v1, vcc
	v_add_co_u32_e32 v0, vcc, 0x8000, v0
	s_nop 1
	v_addc_co_u32_e32 v1, vcc, 0, v1, vcc
	global_load_dwordx4 v[112:115], v[2:3], off
	global_load_dwordx4 v[116:119], v[0:1], off offset:1536
	v_and_b32_e32 v0, 0xc0, v188
	v_cmp_eq_u32_e32 vcc, 0, v0
	v_mov_b32_e32 v0, 0
	s_and_saveexec_b64 s[2:3], vcc
	s_cbranch_execz .LBB0_296
	v_mul_u32_u24_e32 v1, 0x3b00, v7
	v_lshlrev_b32_e32 v64, 1, v1
	v_lshl_add_u64 v[2:3], s[70:71], 0, v[64:65]
	v_lshl_add_u64 v[2:3], v[154:155], 1, v[2:3]
	v_add_co_u32_e32 v2, vcc, 0x7000, v2
	s_nop 1
	v_addc_co_u32_e32 v3, vcc, 0, v3, vcc
	global_load_ushort v1, v[2:3], off offset:1024
	s_waitcnt vmcnt(0)
	v_lshlrev_b32_e32 v191, 16, v1
	v_mov_b32_e32 v237, v1

; DI void ssd_pair_item(const Params& P, unsigned char* smem, int b, int hp) {
;     ...
;         if (wl == 0) {
;             const float r0 = dr0 + dtb;
;             const float d0 = r0 > 20.f ? r0 : log1pf(__expf(r0));
;             float c0 = d0 * Aneg;
; #pragma unroll
;             for (int o = 1; o < 64; o <<= 1) { const float a0 = __shfl_up(c0, o); if (lane >= o) c0 += a0; }
;             const float last = __shfl(c0, 63);
;             cum[lane] = c0; dtv[lane] = d0; wsc[lane] = d0 * __expf(last - c0);
;         }
.LBB0_298:
	v_mov_b32_e32 v32, v188
	s_waitcnt lgkmcnt(0)
	s_barrier
	v_bfe_u32 v33, v32, 6, 2
	v_and_b32_e32 v58, 63, v32
	v_cmp_eq_u32_e64 s[2:3], 0, v33
	s_and_saveexec_b64 s[4:5], s[2:3]
	s_cbranch_execz .LBB0_302
	s_waitcnt vmcnt(9)
	v_lshlrev_b32_e32 v191, 16, v237
	v_add_f32_e32 v34, v189, v191
	s_mov_b32 s0, 0x41a00000
	v_cmp_nlt_f32_e32 vcc, s0, v34
	s_and_saveexec_b64 s[74:75], vcc
	s_cbranch_execz .LBB0_301
	v_mul_f32_e32 v34, 0x3fb8aa3b, v34
	v_exp_f32_e32 v48, v34
	s_mov_b32 s0, 0x3f2aaaab
	v_add_f32_e32 v36, 1.0, v48
	v_frexp_mant_f32_e32 v38, v36
	v_cvt_f64_f32_e32 v[34:35], v36
	v_frexp_exp_i32_f64_e32 v34, v[34:35]
	v_cmp_gt_f32_e32 vcc, s0, v38
	v_add_f32_e32 v37, -1.0, v36
	v_sub_f32_e32 v39, v37, v36
	v_subbrev_co_u32_e32 v42, vcc, 0, v34, vcc
	v_sub_u32_e32 v34, 0, v42
	v_sub_f32_e32 v37, v48, v37
	v_add_f32_e32 v39, 1.0, v39
	v_ldexp_f32 v35, v36, v34
	v_add_f32_e32 v37, v37, v39
	v_add_f32_e32 v36, -1.0, v35
	v_add_f32_e32 v38, 1.0, v35
	v_ldexp_f32 v34, v37, v34
	v_add_f32_e32 v37, 1.0, v36
	v_add_f32_e32 v39, -1.0, v38
	v_sub_f32_e32 v37, v35, v37
	v_sub_f32_e32 v35, v35, v39
	v_add_f32_e32 v37, v34, v37
	v_add_f32_e32 v34, v34, v35
	v_add_f32_e32 v43, v38, v34
	v_rcp_f32_e32 v45, v43
	v_sub_f32_e32 v35, v43, v38
	v_sub_f32_e32 v44, v34, v35
	v_add_f32_e32 v35, v36, v37
	v_mul_f32_e32 v47, v35, v45
	v_sub_f32_e32 v34, v35, v36
	v_mul_f32_e32 v36, v43, v47
	v_fma_f32 v38, v47, v43, -v36
	v_fmac_f32_e32 v38, v47, v44
	v_sub_f32_e32 v46, v37, v34
	v_add_f32_e32 v34, v36, v38
	v_sub_f32_e32 v37, v35, v34
	v_pk_add_f32 v[40:41], v[34:35], v[36:37] neg_lo:[0,1] neg_hi:[0,1]
	v_mov_b32_e32 v39, v34
	v_pk_add_f32 v[34:35], v[40:41], v[38:39] neg_lo:[0,1] neg_hi:[0,1]
	s_mov_b32 s0, 0x3f317218
	v_add_f32_e32 v35, v46, v35
	v_add_f32_e32 v34, v34, v35
	v_add_f32_e32 v35, v37, v34
	v_mul_f32_e32 v46, v45, v35
	v_mul_f32_e32 v36, v43, v46
	v_fma_f32 v38, v46, v43, -v36
	v_fmac_f32_e32 v38, v46, v44
	v_sub_f32_e32 v37, v37, v35
	v_add_f32_e32 v43, v34, v37
	v_add_f32_e32 v34, v36, v38
	v_sub_f32_e32 v37, v35, v34
	v_pk_add_f32 v[40:41], v[34:35], v[36:37] neg_lo:[0,1] neg_hi:[0,1]
	v_mov_b32_e32 v39, v34
	v_pk_add_f32 v[34:35], v[40:41], v[38:39] neg_lo:[0,1] neg_hi:[0,1]
	v_cmp_neq_f32_e32 vcc, s89, v48
	v_add_f32_e32 v35, v43, v35
	v_add_f32_e32 v34, v34, v35
	v_add_f32_e32 v35, v47, v46
	v_add_f32_e32 v34, v37, v34
	v_sub_f32_e32 v36, v35, v47
	v_mul_f32_e32 v34, v45, v34
	v_sub_f32_e32 v36, v46, v36
	v_add_f32_e32 v36, v36, v34
	v_add_f32_e32 v38, v35, v36
	v_mul_f32_e32 v39, v38, v38
	v_fmamk_f32 v34, v39, 0x3e9b6dac, v180
	v_fmaak_f32 v153, v39, v34, 0x3f2aaada
	v_cvt_f32_i32_e32 v34, v42
	v_sub_f32_e32 v35, v38, v35
	v_sub_f32_e32 v35, v36, v35
	v_ldexp_f32 v40, v35, 1
	v_mul_f32_e32 v35, v38, v39
	v_ldexp_f32 v37, v38, 1
	v_pk_mul_f32 v[38:39], v[34:35], v[152:153]
	s_nop 0
	v_fma_f32 v36, v34, s0, -v38
	v_fmac_f32_e32 v36, 0xb102e308, v34
	v_pk_add_f32 v[34:35], v[38:39], v[36:37]
	s_nop 0
	v_sub_f32_e32 v37, v35, v37
	v_sub_f32_e32 v37, v39, v37
	v_add_f32_e32 v41, v40, v37
	v_mov_b32_e32 v40, v38
	v_pk_add_f32 v[38:39], v[34:35], v[38:39] neg_lo:[0,1] neg_hi:[0,1]
	v_pk_add_f32 v[42:43], v[34:35], v[40:41]
	v_mov_b32_e32 v37, v34
	v_mov_b32_e32 v39, v43
	v_pk_add_f32 v[44:45], v[36:37], v[38:39] neg_lo:[0,1] neg_hi:[0,1]
	v_pk_add_f32 v[36:37], v[36:37], v[38:39]
	v_mov_b32_e32 v40, v41
	v_pk_add_f32 v[38:39], v[36:37], v[34:35] op_sel:[1,0] op_sel_hi:[0,1] neg_lo:[0,1] neg_hi:[0,1]
	v_pk_add_f32 v[46:47], v[42:43], v[38:39] op_sel_hi:[1,0] neg_lo:[0,1] neg_hi:[0,1]
	v_mov_b32_e32 v42, v43
	v_mov_b32_e32 v43, v37
	v_pk_mov_b32 v[38:39], v[34:35], v[38:39] op_sel:[1,0]
	v_mov_b32_e32 v41, v34
	v_pk_add_f32 v[38:39], v[42:43], v[38:39] neg_lo:[0,1] neg_hi:[0,1]
	v_mov_b32_e32 v46, v44
	v_pk_add_f32 v[34:35], v[40:41], v[38:39] neg_lo:[0,1] neg_hi:[0,1]
	v_mov_b32_e32 v45, v37
	v_pk_add_f32 v[38:39], v[46:47], v[34:35]
	s_nop 0
	v_pk_add_f32 v[40:41], v[38:39], v[38:39] op_sel:[0,1] op_sel_hi:[1,0]
	s_nop 0
	v_pk_add_f32 v[36:37], v[36:37], v[40:41] op_sel:[1,0] op_sel_hi:[0,1]
	v_mov_b32_e32 v39, v36
	v_pk_add_f32 v[42:43], v[38:39], v[44:45] neg_lo:[0,1] neg_hi:[0,1]
	v_mov_b32_e32 v35, v40
	v_sub_f32_e32 v37, v38, v42
	v_pk_add_f32 v[34:35], v[34:35], v[42:43] neg_lo:[0,1] neg_hi:[0,1]
	v_sub_f32_e32 v37, v44, v37
	v_add_f32_e32 v34, v34, v37
	v_add_f32_e32 v34, v34, v35
	v_add_f32_e32 v34, v36, v34
	v_cndmask_b32_e32 v34, v184, v34, vcc
	v_cmp_ngt_f32_e32 vcc, -1.0, v48
	s_nop 1
	v_cndmask_b32_e32 v34, v185, v34, vcc
	v_cmp_neq_f32_e32 vcc, -1.0, v48
	s_nop 1
	v_cndmask_b32_e32 v34, v186, v34, vcc
	v_cmp_lt_f32_e64 vcc, |v48|, s90
	s_nop 1
	v_cndmask_b32_e32 v34, v34, v48, vcc

; DI int opaque_i(int v) { asm volatile("" : "+v"(v)); return v; }
; #define MFMA32(a, b, c) __builtin_amdgcn_mfma_f32_32x32x16_bf16((a), (b), (c), 0, 0, 0)
; DI void ssd_pair_item(const Params& P, unsigned char* smem, int b, int hp) {
;     ...
;             const int l32 = opaque_i(l32o), hh = opaque_i(hho);
;             const int l = 32 * lt + l32;
;             const unsigned char* cfp = smem + S2_CS + l * RS + 16 * hh;
;     ...
;             f32x16 acc;
; #pragma unroll
;             for (int i = 0; i < 16; ++i) acc[i] = 0.f;
; #pragma unroll
;             for (int ks = 0; ks < 8; ++ks) { const bf16x8 a = *(const bf16x8*)(hb + S2_ST + (32 * ph + l32) * RS + (16 * ks + 8 * hh) * 2); acc = MFMA32(a, CF2(ks), acc); }
;             const float cl = cum[l];
;             { const float e = __expf(cl);
; #pragma unroll
;               for (int i = 0; i < 16; ++i) acc[i] *= e; }
.LBB0_311:
	s_or_b64 exec, exec, s[74:75]
	v_or_b32_e32 v32, v60, v158
	v_lshl_add_u32 v40, v59, 1, s82
	v_add_u32_e32 v36, 61, v40
	v_ashrrev_i32_e32 v33, 31, v32
	v_mov_b64_e32 v[34:35], s[70:71]
	v_mad_u64_u32 v[36:37], s[0:1], v36, s83, v[34:35]
	v_lshlrev_b64 v[32:33], 1, v[32:33]
	v_lshl_add_u64 v[36:37], v[36:37], 0, v[32:33]
	v_add_u32_e32 v38, 62, v40
	v_add_co_u32_e32 v36, vcc, 0x1000, v36
	v_mad_u64_u32 v[38:39], s[0:1], v38, s83, v[34:35]
	s_nop 0
	v_addc_co_u32_e32 v37, vcc, 0, v37, vcc
	v_lshl_add_u64 v[38:39], v[38:39], 0, v[32:33]
	v_add_co_u32_e32 v38, vcc, 0x1000, v38
	s_nop 1
	v_addc_co_u32_e32 v39, vcc, 0, v39, vcc
	global_load_dwordx4 v[100:103], v[36:37], off
	global_load_dwordx4 v[104:107], v[38:39], off
	v_add_u32_e32 v36, 63, v40
	v_mad_u64_u32 v[36:37], s[0:1], v36, s83, v[34:35]
	v_lshl_add_u64 v[36:37], v[36:37], 0, v[32:33]
	v_add_u32_e32 v38, 64, v40
	v_add_co_u32_e32 v36, vcc, 0x1000, v36
	v_mad_u64_u32 v[38:39], s[0:1], v38, s83, v[34:35]
	s_nop 0
	v_addc_co_u32_e32 v37, vcc, 0, v37, vcc
	v_lshl_add_u64 v[38:39], v[38:39], 0, v[32:33]
	v_add_co_u32_e32 v38, vcc, 0x1000, v38
	s_nop 1
	v_addc_co_u32_e32 v39, vcc, 0, v39, vcc
	global_load_dwordx4 v[108:111], v[36:37], off
	global_load_dwordx4 v[112:115], v[38:39], off
	v_add_u32_e32 v36, 0x41, v40
	v_mad_u64_u32 v[34:35], s[0:1], v36, s83, v[34:35]
	v_lshl_add_u64 v[32:33], v[34:35], 0, v[32:33]
	v_add_co_u32_e32 v32, vcc, 0x1000, v32
	s_nop 1
	v_addc_co_u32_e32 v33, vcc, 0, v33, vcc
	global_load_dwordx4 v[116:119], v[32:33], off
	v_or_b32_e32 v32, s85, v58
	v_mul_lo_u32 v64, v32, s87
	v_lshl_add_u64 v[32:33], v[64:65], 1, s[70:71]
	v_lshl_add_u64 v[32:33], v[154:155], 1, v[32:33]
	v_add_co_u32_e32 v32, vcc, 0x7000, v32
	s_nop 1
	v_addc_co_u32_e32 v33, vcc, 0, v33, vcc
	global_load_ushort v237, v[32:33], off offset:1024
.LBB0_313:
.LBB0_314:
	v_mov_b32_e32 v202, v195
	v_lshlrev_b32_e32 v201, 5, v198
	v_add_u32_e32 v175, 1, v198
	v_add_u32_e32 v174, v202, v201
	v_mul_lo_u32 v32, v174, s84
	v_lshlrev_b32_e32 v172, 4, v200
	v_add_u32_e32 v203, v202, v197
	v_add3_u32 v52, 0, v32, v172
	v_mul_lo_u32 v32, v203, s84
	v_add3_u32 v53, v192, v32, v172
	ds_read_b128 v[120:123], v52 offset:17408
	ds_read_b128 v[124:127], v52 offset:17440
	ds_read_b128 v[32:35], v53 offset:62464
	ds_read_b128 v[48:51], v53 offset:62496
	s_waitcnt lgkmcnt(1)
	v_mfma_f32_32x32x16_bf16 v[32:47], v[32:35], v[120:123], 0
	v_lshlrev_b32_e32 v204, 2, v200
	v_mad_u64_u32 v[176:177], s[0:1], v202, s84, v[172:173]
	v_mov_b32_e32 v153, v174
	v_add_u32_e32 v206, v190, v172
	s_mov_b64 s[2:3], 0
	v_mov_b32_e32 v177, v204
	s_waitcnt lgkmcnt(0)
	v_mfma_f32_32x32x16_bf16 v[32:47], v[48:51], v[124:127], v[32:47]
	ds_read_b128 v[48:51], v53 offset:62528
	ds_read_b128 v[128:131], v52 offset:17472
	s_waitcnt lgkmcnt(0)
	v_mfma_f32_32x32x16_bf16 v[32:47], v[48:51], v[128:131], v[32:47]
	ds_read_b128 v[48:51], v53 offset:62560
	ds_read_b128 v[132:135], v52 offset:17504
	s_waitcnt lgkmcnt(0)
	v_mfma_f32_32x32x16_bf16 v[32:47], v[48:51], v[132:135], v[32:47]
	ds_read_b128 v[48:51], v53 offset:62592
	ds_read_b128 v[136:139], v52 offset:17536
	s_waitcnt lgkmcnt(0)
	v_mfma_f32_32x32x16_bf16 v[32:47], v[48:51], v[136:139], v[32:47]
	ds_read_b128 v[48:51], v53 offset:62624
	ds_read_b128 v[140:143], v52 offset:17568
	s_waitcnt lgkmcnt(0)
	v_mfma_f32_32x32x16_bf16 v[32:47], v[48:51], v[140:143], v[32:47]
	ds_read_b128 v[48:51], v53 offset:62656
	ds_read_b128 v[144:147], v52 offset:17600
	s_waitcnt lgkmcnt(0)
	v_mfma_f32_32x32x16_bf16 v[32:47], v[48:51], v[144:147], v[32:47]
	ds_read_b128 v[48:51], v53 offset:62688
	ds_read_b128 v[148:151], v52 offset:17632
	s_waitcnt lgkmcnt(0)
	v_mfma_f32_32x32x16_bf16 v[32:47], v[48:51], v[148:151], v[32:47]
	v_lshl_add_u32 v48, v174, 2, v193
	ds_read_b32 v64, v48 offset:45056
	v_mul_lo_u32 v50, v202, s92
	s_waitcnt lgkmcnt(0)
	v_mul_f32_e32 v48, 0x3fb8aa3b, v64
	v_exp_f32_e32 v48, v48
	s_nop 5
	v_pk_mul_f32 v[46:47], v[46:47], v[48:49] op_sel_hi:[1,0]
	v_pk_mul_f32 v[44:45], v[44:45], v[48:49] op_sel_hi:[1,0]
	v_pk_mul_f32 v[42:43], v[42:43], v[48:49] op_sel_hi:[1,0]
	v_pk_mul_f32 v[40:41], v[40:41], v[48:49] op_sel_hi:[1,0]
	v_pk_mul_f32 v[38:39], v[38:39], v[48:49] op_sel_hi:[1,0]
	v_pk_mul_f32 v[36:37], v[36:37], v[48:49] op_sel_hi:[1,0]
	v_pk_mul_f32 v[34:35], v[34:35], v[48:49] op_sel_hi:[1,0]
	v_pk_mul_f32 v[32:33], v[32:33], v[48:49] op_sel_hi:[1,0]
	v_lshlrev_b32_e32 v48, 3, v200
	v_mad_u32_u24 v49, v199, s93, v194
	v_add3_u32 v205, v49, v50, v48
; #define MFMA32(a, b, c) __builtin_amdgcn_mfma_f32_32x32x16_bf16((a), (b), (c), 0, 0, 0)
; DI bf16x8 cat44(s16x4 a, s16x4 b) { return __builtin_shufflevector(a, b, 0, 1, 2, 3, 4, 5, 6, 7); }
; DI void ssd_pair_item(const Params& P, unsigned char* smem, int b, int hp) {
;     ...
;             for (int st = 0; st <= lt; ++st) {
;                 f32x16 S;
; #pragma unroll
;                 for (int i = 0; i < 16; ++i) S[i] = 0.f;
; #pragma unroll
;                 for (int ks = 0; ks < 8; ++ks) { const bf16x8 a = *(const bf16x8*)(smem + S2_BS + (32 * st + l32) * RS + (16 * ks + 8 * hh) * 2); S = MFMA32(a, CF2(ks), S); }
; #pragma unroll
;                 for (int ig = 0; ig < 4; ++ig) { const int s0 = 32 * st + 8 * ig + 4 * hh; const f32x4 cs = *(const f32x4*)(cum + s0), dv = *(const f32x4*)(dtv + s0);
; #pragma unroll
;                     for (int j = 0; j < 4; ++j) { const float dec = __expf(fminf(cl - cs[j], 0.f)) * dv[j]; S[4 * ig + j] = (s0 + j <= l) ? S[4 * ig + j] * dec : 0.f; } }
; #pragma unroll
;                 for (int s2 = 0; s2 < 2; ++s2) {
;                     const bf16x8 mf = pack8(S, s2);
;                     const unsigned char* xp = hb + S2_XT + (32 * ph + l32) * RS2 + (32 * st + 16 * s2 + 4 * hh) * 2;
;                     const bf16x8 a = cat44(*(const s16x4*)xp, *(const s16x4*)(xp + 16));
;                     acc = MFMA32(a, mf, acc);
;                 }
;             }
.LBB0_315:
	v_add_u32_e32 v207, 0, v176
	ds_read_b128 v[48:51], v207
	ds_read_b128 v[208:211], v207 offset:32
	v_add_u32_e32 v212, 0, v206
	v_cmp_le_i32_e32 vcc, v177, v174
	v_add_u32_e32 v175, -1, v175
	s_waitcnt lgkmcnt(1)
	v_mfma_f32_32x32x16_bf16 v[48:63], v[48:51], v[120:123], 0
	v_add_u32_e32 v206, 0x80, v206
	v_add_u32_e32 v176, 0x2200, v176
	s_waitcnt lgkmcnt(0)
	v_mfma_f32_32x32x16_bf16 v[48:63], v[208:211], v[124:127], v[48:63]
	ds_read_b128 v[208:211], v207 offset:64
	s_waitcnt lgkmcnt(0)
	v_mfma_f32_32x32x16_bf16 v[48:63], v[208:211], v[128:131], v[48:63]
	ds_read_b128 v[208:211], v207 offset:96
	s_waitcnt lgkmcnt(0)
	v_mfma_f32_32x32x16_bf16 v[48:63], v[208:211], v[132:135], v[48:63]
	ds_read_b128 v[208:211], v207 offset:128
	s_waitcnt lgkmcnt(0)
	v_mfma_f32_32x32x16_bf16 v[48:63], v[208:211], v[136:139], v[48:63]
	ds_read_b128 v[208:211], v207 offset:160
	s_waitcnt lgkmcnt(0)
	v_mfma_f32_32x32x16_bf16 v[48:63], v[208:211], v[140:143], v[48:63]
	ds_read_b128 v[208:211], v207 offset:192
	s_waitcnt lgkmcnt(0)
	v_mfma_f32_32x32x16_bf16 v[48:63], v[208:211], v[144:147], v[48:63]
	ds_read_b128 v[208:211], v207 offset:224
	v_add_u32_e32 v207, 0x13800, v212
	s_waitcnt lgkmcnt(0)
	v_mfma_f32_32x32x16_bf16 v[48:63], v[208:211], v[148:151], v[48:63]
	ds_read_b128 v[208:211], v207
	v_add_u32_e32 v207, 0x13a00, v212
	ds_read_b128 v[216:219], v207
	s_waitcnt lgkmcnt(1)
	v_sub_f32_e32 v207, v64, v208
	v_min_f32_e32 v207, 0, v207
	v_mul_f32_e32 v207, 0x3fb8aa3b, v207
	v_exp_f32_e32 v207, v207
	s_waitcnt lgkmcnt(0)
	v_mul_f32_e32 v207, v216, v207
	s_nop 1
	v_mul_f32_e32 v48, v48, v207
	v_cndmask_b32_e32 v208, 0, v48, vcc
	v_sub_f32_e32 v48, v64, v209
	v_min_f32_e32 v48, 0, v48
	v_mul_f32_e32 v48, 0x3fb8aa3b, v48
	v_exp_f32_e32 v48, v48
	v_cmp_lt_i32_e32 vcc, v177, v174
	v_add_u32_e32 v207, 8, v177
	v_mul_f32_e32 v48, v217, v48
	v_mul_f32_e32 v48, v49, v48
	v_cndmask_b32_e32 v209, 0, v48, vcc
	v_sub_f32_e32 v48, v64, v210
	v_sub_f32_e32 v49, v64, v211
	v_min_f32_e32 v48, 0, v48
	v_min_f32_e32 v49, 0, v49
	v_mul_f32_e32 v48, 0x3fb8aa3b, v48
	v_mul_f32_e32 v49, 0x3fb8aa3b, v49
	v_exp_f32_e32 v48, v48
	v_exp_f32_e32 v49, v49
	v_cmp_le_i32_e32 vcc, v207, v174
	v_or_b32_e32 v211, 2, v177
	v_or_b32_e32 v210, 3, v177
	v_pk_mul_f32 v[48:49], v[218:219], v[48:49]
	v_cvt_pk_bf16_f32 v208, v208, v209
	v_pk_mul_f32 v[48:49], v[50:51], v[48:49]
	v_add_u32_e32 v50, 0x13820, v212
	ds_read_b128 v[216:219], v50
	v_add_u32_e32 v50, 0x13a20, v212
	ds_read_b128 v[220:223], v50
	v_cvt_pk_bf16_f32 v48, v48, v49
	s_waitcnt lgkmcnt(1)
	v_sub_f32_e32 v50, v64, v216
	v_min_f32_e32 v50, 0, v50
	v_mul_f32_e32 v50, 0x3fb8aa3b, v50
	v_exp_f32_e32 v50, v50
	v_sub_f32_e32 v51, v64, v219
	v_min_f32_e32 v51, 0, v51
	v_mul_f32_e32 v51, 0x3fb8aa3b, v51
	s_waitcnt lgkmcnt(0)
	v_mul_f32_e32 v50, v220, v50
	v_mul_f32_e32 v50, v52, v50
	v_cndmask_b32_e32 v213, 0, v50, vcc
	v_sub_f32_e32 v50, v64, v217
	v_min_f32_e32 v50, 0, v50
	v_mul_f32_e32 v50, 0x3fb8aa3b, v50
	v_exp_f32_e32 v50, v50
	v_cmp_lt_i32_e32 vcc, v207, v174
	v_exp_f32_e32 v51, v51
	v_add_u32_e32 v52, 0x13840, v212
	v_mul_f32_e32 v50, v221, v50
	v_mul_f32_e32 v50, v53, v50
	v_cndmask_b32_e32 v214, 0, v50, vcc
	v_sub_f32_e32 v50, v64, v218
	v_min_f32_e32 v50, 0, v50
	v_mul_f32_e32 v50, 0x3fb8aa3b, v50
	v_exp_f32_e32 v50, v50
	v_add_u32_e32 v216, 0x13a40, v212
	ds_read_b128 v[216:219], v216
	v_or_b32_e32 v220, 3, v207
	v_pk_mul_f32 v[50:51], v[222:223], v[50:51]
	v_or_b32_e32 v221, 2, v207
	v_pk_mul_f32 v[50:51], v[54:55], v[50:51]
	ds_read_b128 v[52:55], v52
	v_add_u32_e32 v207, 16, v177
	v_cmp_le_i32_e32 vcc, v207, v174
	v_add_u32_e32 v223, 24, v177
	v_add_u32_e32 v177, 32, v177
	s_waitcnt lgkmcnt(0)
	v_sub_f32_e32 v52, v64, v52
	v_min_f32_e32 v52, 0, v52
	v_sub_f32_e32 v53, v64, v53
	v_mul_f32_e32 v52, 0x3fb8aa3b, v52
	v_min_f32_e32 v53, 0, v53
	v_exp_f32_e32 v52, v52
	v_mul_f32_e32 v53, 0x3fb8aa3b, v53
	v_exp_f32_e32 v53, v53
	v_mul_f32_e32 v52, v216, v52
	v_mul_f32_e32 v52, v56, v52
	v_mul_f32_e32 v53, v217, v53
	v_cndmask_b32_e32 v52, 0, v52, vcc
	v_cmp_lt_i32_e32 vcc, v207, v174
	v_mul_f32_e32 v53, v57, v53
	v_add_u32_e32 v56, 0x13860, v212
	v_cndmask_b32_e32 v222, 0, v53, vcc
	v_sub_f32_e32 v53, v64, v54
	v_min_f32_e32 v53, 0, v53
	v_mul_f32_e32 v53, 0x3fb8aa3b, v53
	v_exp_f32_e32 v54, v53
	v_sub_f32_e32 v53, v64, v55
	v_min_f32_e32 v53, 0, v53
	v_mul_f32_e32 v53, 0x3fb8aa3b, v53
	v_exp_f32_e32 v55, v53
	v_add_u32_e32 v212, 0x13a60, v212
	v_cmp_le_i32_e32 vcc, v223, v174
	v_or_b32_e32 v53, 3, v207
	v_pk_mul_f32 v[54:55], v[218:219], v[54:55]
	ds_read_b128 v[216:219], v212
	v_pk_mul_f32 v[54:55], v[58:59], v[54:55]
	ds_read_b128 v[56:59], v56
	v_or_b32_e32 v207, 2, v207
	v_cvt_pk_bf16_f32 v54, v54, v55
	v_cvt_pk_bf16_f32 v52, v52, v222
	s_waitcnt lgkmcnt(0)
	v_sub_f32_e32 v56, v64, v56
	v_min_f32_e32 v56, 0, v56
	v_mul_f32_e32 v56, 0x3fb8aa3b, v56
	v_exp_f32_e32 v56, v56
	s_nop 0
	v_mul_f32_e32 v56, v216, v56
	v_mul_f32_e32 v56, v60, v56
	v_cndmask_b32_e32 v60, 0, v56, vcc
	v_sub_f32_e32 v56, v64, v57
	v_min_f32_e32 v56, 0, v56
	v_mul_f32_e32 v56, 0x3fb8aa3b, v56
	v_exp_f32_e32 v56, v56
	v_cmp_lt_i32_e32 vcc, v223, v174
	v_sub_f32_e32 v57, v64, v59
	v_min_f32_e32 v57, 0, v57
	v_mul_f32_e32 v56, v217, v56
	v_mul_f32_e32 v56, v61, v56
	v_cndmask_b32_e32 v61, 0, v56, vcc
	v_sub_f32_e32 v56, v64, v58
	v_min_f32_e32 v56, 0, v56
	v_mul_f32_e32 v56, 0x3fb8aa3b, v56
	v_mul_f32_e32 v57, 0x3fb8aa3b, v57
	v_exp_f32_e32 v56, v56
	v_exp_f32_e32 v57, v57
	v_cmp_le_i32_e32 vcc, v211, v174
	v_or_b32_e32 v59, 2, v223
	v_or_b32_e32 v58, 3, v223
	v_cndmask_b32_e32 v49, 0, v48, vcc
	v_lshrrev_b32_e32 v48, 16, v48
	v_cmp_le_i32_e32 vcc, v210, v153
	v_pk_mul_f32 v[56:57], v[218:219], v[56:57]
	v_cvt_pk_bf16_f32 v210, v213, v214
	v_cndmask_b32_e32 v48, 0, v48, vcc
	v_perm_b32 v209, v48, v49, s94
	v_cvt_pk_bf16_f32 v48, v50, v51
	v_cmp_le_i32_e32 vcc, v221, v174
	v_pk_mul_f32 v[56:57], v[62:63], v[56:57]
	v_add_u32_e32 v62, 0, v205
	v_cndmask_b32_e32 v49, 0, v48, vcc
	v_lshrrev_b32_e32 v48, 16, v48
	v_cmp_le_i32_e32 vcc, v220, v153
	v_add_u32_e32 v205, 64, v205
	s_nop 0
	v_cndmask_b32_e32 v48, 0, v48, vcc
	v_perm_b32 v211, v48, v49, s94
	ds_read2_b64 v[216:219], v62 offset1:2
	ds_read2_b64 v[48:51], v62 offset0:4 offset1:6
	s_waitcnt lgkmcnt(1)
	v_mfma_f32_32x32x16_bf16 v[32:47], v[216:219], v[208:211], v[32:47]
	v_cmp_le_i32_e32 vcc, v207, v174
	s_nop 1
	v_cndmask_b32_e32 v55, 0, v54, vcc
	v_lshrrev_b32_e32 v54, 16, v54
	v_cmp_le_i32_e32 vcc, v53, v153
	s_nop 1
	v_cndmask_b32_e32 v53, 0, v54, vcc
	v_perm_b32 v53, v53, v55, s94
	v_cvt_pk_bf16_f32 v55, v56, v57
	v_cmp_le_i32_e32 vcc, v59, v174
	v_cvt_pk_bf16_f32 v54, v60, v61
	s_nop 0
	v_cndmask_b32_e32 v56, 0, v55, vcc
	v_lshrrev_b32_e32 v55, 16, v55
	v_cmp_le_i32_e32 vcc, v58, v153
	s_nop 1
	v_cndmask_b32_e32 v55, 0, v55, vcc
	v_perm_b32 v55, v55, v56, s94
	v_cmp_eq_u32_e32 vcc, 0, v175
	s_or_b64 s[2:3], vcc, s[2:3]
	s_waitcnt lgkmcnt(0)
	v_mfma_f32_32x32x16_bf16 v[32:47], v[48:51], v[52:55], v[32:47]
	s_andn2_b64 exec, exec, s[2:3]
	s_cbranch_execnz .LBB0_315
; DI float bf2f(bf16_t u) { return __uint_as_float(((unsigned)u) << 16); }
; DI unsigned pk2(float lo, float hi) { f32x2 v = {lo, hi}; bf16x2_t b = __builtin_convertvector(v, bf16x2_t); return __builtin_bit_cast(unsigned, b); }
; DI float lo16(unsigned u) { return __uint_as_float(u << 16); }
; DI float hi16(unsigned u) { return __uint_as_float(u & 0xffff0000u); }
; DI float siluf_(float x) { return x * __builtin_amdgcn_rcpf(1.f + __expf(-x)); }
; DI int opaque_i(int v) { asm volatile("" : "+v"(v)); return v; }
; DI void ssd_pair_item(const Params& P, unsigned char* smem, int b, int hp) {
;     ...
;             const size_t tok = (size_t)b * TT + t0 + l; float ss = 0.f;
;             const int xo = opaque_i((32 * ph + 4 * hh) * RS2 + l * 2);
; #pragma unroll
;             for (int ig = 0; ig < 4; ++ig) { const int p0 = 32 * ph + 8 * ig + 4 * hh;
;                 const u32x2 zz = zr[ig];
;                 const float zf[4] = {lo16(zz.x), hi16(zz.x), lo16(zz.y), hi16(zz.y)}; float y[4];
; #pragma unroll
;                 for (int j = 0; j < 4; ++j) { const float xv = bf2f(*(const bf16_t*)(hb + S2_XT + xo + (8 * ig + j) * RS2)); y[j] = (acc[4 * ig + j] + Dsk * xv) * siluf_(zf[j]); ss += y[j] * y[j]; }
;                 u32x2 w; w.x = pk2(y[0], y[1]); w.y = pk2(y[2], y[3]);
;                 *(u32x2*)(P_yg + tok * 4096 + hd * 64 + p0) = w; }
	s_or_b64 exec, exec, s[2:3]
	v_add_u32_e32 v52, v204, v197
	v_mul_lo_u32 v50, v52, s92
	v_lshl_add_u32 v50, v174, 1, v50
	s_cmp_eq_u32 s33, 31
	s_cbranch_scc1 .Lssd_wA_0
	s_waitcnt vmcnt(17)
	s_branch .Lssd_wB_0
.Lssd_wA_0:
	s_waitcnt vmcnt(3)
.Lssd_wB_0:
	v_and_b32_e32 v51, 0xffff0000, v162
	v_add_u32_e32 v54, v192, v50
	v_lshlrev_b32_e32 v50, 16, v162
	v_mul_f32_e32 v53, 0xbfb8aa3b, v50
	v_exp_f32_e32 v53, v53
	v_mul_f32_e32 v55, 0xbfb8aa3b, v51
	v_exp_f32_e32 v55, v55
	s_add_u32 s0, s72, s82
	v_add_f32_e32 v53, 1.0, v53
	v_rcp_f32_e32 v58, v53
	v_add_f32_e32 v53, 1.0, v55
	v_rcp_f32_e32 v59, v53
	ds_read_u16 v53, v54 offset:53248
	ds_read_u16 v55, v54 offset:53392
	ds_read_u16 v62, v54 offset:53536
	ds_read_u16 v63, v54 offset:53680
	ds_read_u16 v64, v54 offset:54400
	ds_read_u16 v120, v54 offset:54544
	ds_read_u16 v121, v54 offset:54688
	ds_read_u16 v122, v54 offset:54832
	s_waitcnt lgkmcnt(6)
	v_lshlrev_b32_e32 v61, 16, v55
	v_lshlrev_b32_e32 v60, 16, v53
	v_pk_fma_f32 v[32:33], v[156:157], v[60:61], v[32:33]
	v_pk_mul_f32 v[50:51], v[58:59], v[50:51]
	v_lshlrev_b32_e32 v58, 16, v163
	v_pk_mul_f32 v[32:33], v[50:51], v[32:33]
	v_and_b32_e32 v59, 0xffff0000, v163
	v_mul_f32_e32 v50, 0xbfb8aa3b, v58
	v_exp_f32_e32 v53, v50
	v_mul_f32_e32 v50, 0xbfb8aa3b, v59
	v_exp_f32_e32 v55, v50
	v_ashrrev_i32_e32 v175, 31, v174
	v_add_f32_e32 v53, 1.0, v53
	v_rcp_f32_e32 v60, v53
	v_add_f32_e32 v53, 1.0, v55
	v_rcp_f32_e32 v61, v53
	s_addc_u32 s1, s73, 0
	v_lshl_add_u64 v[48:49], s[0:1], 0, v[174:175]
	v_lshlrev_b64 v[56:57], 13, v[48:49]
	v_pk_mul_f32 v[50:51], v[32:33], v[32:33]
	v_pk_mul_f32 v[58:59], v[60:61], v[58:59]
	v_cvt_pk_bf16_f32 v60, v32, v33
	v_lshl_add_u64 v[32:33], v[160:161], 0, v[56:57]
	v_ashrrev_i32_e32 v53, 31, v52
	v_lshl_add_u64 v[32:33], v[52:53], 1, v[32:33]
	s_cmp_eq_u32 s33, 31
	s_cbranch_scc1 .Lssd_wA_1
	s_waitcnt vmcnt(16)
	s_branch .Lssd_wB_1
.Lssd_wA_1:
	s_waitcnt vmcnt(2)
.Lssd_wB_1:
	v_lshlrev_b32_e32 v52, 16, v166
	v_and_b32_e32 v53, 0xffff0000, v166
	v_mul_f32_e32 v55, 0xbfb8aa3b, v52
	v_exp_f32_e32 v55, v55
	v_mul_f32_e32 v56, 0xbfb8aa3b, v53
	v_exp_f32_e32 v57, v56
	s_waitcnt lgkmcnt(4)
	v_lshlrev_b32_e32 v63, 16, v63
	v_add_f32_e32 v55, 1.0, v55
	v_rcp_f32_e32 v56, v55
	v_add_f32_e32 v55, 1.0, v57
	v_lshlrev_b32_e32 v62, 16, v62
	v_rcp_f32_e32 v57, v55
	v_pk_fma_f32 v[34:35], v[156:157], v[62:63], v[34:35]
	v_add_f32_e32 v50, v50, v51
	v_pk_mul_f32 v[58:59], v[58:59], v[34:35]
	v_pk_mul_f32 v[52:53], v[56:57], v[52:53]
	v_pk_mul_f32 v[34:35], v[58:59], v[58:59]
	v_cvt_pk_bf16_f32 v61, v58, v59
	s_waitcnt lgkmcnt(2)
	v_lshlrev_b32_e32 v59, 16, v120
	v_lshlrev_b32_e32 v58, 16, v64
	v_pk_fma_f32 v[36:37], v[156:157], v[58:59], v[36:37]
	v_lshlrev_b32_e32 v56, 16, v167
	v_pk_mul_f32 v[52:53], v[52:53], v[36:37]
	v_and_b32_e32 v57, 0xffff0000, v167
	v_mul_f32_e32 v36, 0xbfb8aa3b, v56
	v_exp_f32_e32 v55, v36
	v_mul_f32_e32 v36, 0xbfb8aa3b, v57
	v_exp_f32_e32 v59, v36
	global_store_dwordx2 v[32:33], v[60:61], off
	v_add_f32_e32 v55, 1.0, v55
	v_rcp_f32_e32 v58, v55
	v_add_f32_e32 v55, 1.0, v59
	v_rcp_f32_e32 v59, v55
	s_waitcnt lgkmcnt(0)
	v_lshlrev_b32_e32 v61, 16, v122
	v_lshlrev_b32_e32 v60, 16, v121
	v_pk_fma_f32 v[38:39], v[156:157], v[60:61], v[38:39]
	v_pk_mul_f32 v[56:57], v[58:59], v[56:57]
	v_pk_mul_f32 v[36:37], v[52:53], v[52:53]
	v_pk_mul_f32 v[56:57], v[56:57], v[38:39]
	v_cvt_pk_bf16_f32 v52, v52, v53
	v_pk_mul_f32 v[38:39], v[56:57], v[56:57]
	v_cvt_pk_bf16_f32 v53, v56, v57
	s_cmp_eq_u32 s33, 31
	s_cbranch_scc1 .Lssd_wA_2
	s_waitcnt vmcnt(16)
	s_branch .Lssd_wB_2

; DI float bf2f(bf16_t u) { return __uint_as_float(((unsigned)u) << 16); }
; DI unsigned pk2(float lo, float hi) { f32x2 v = {lo, hi}; bf16x2_t b = __builtin_convertvector(v, bf16x2_t); return __builtin_bit_cast(unsigned, b); }
; DI float lo16(unsigned u) { return __uint_as_float(u << 16); }
; DI float hi16(unsigned u) { return __uint_as_float(u & 0xffff0000u); }
; DI float siluf_(float x) { return x * __builtin_amdgcn_rcpf(1.f + __expf(-x)); }
; DI void ssd_pair_item(const Params& P, unsigned char* smem, int b, int hp) {
;     ...
; #pragma unroll
;             for (int ig = 0; ig < 4; ++ig) { const int p0 = 32 * ph + 8 * ig + 4 * hh;
;                 const u32x2 zz = zr[ig];
;                 const float zf[4] = {lo16(zz.x), hi16(zz.x), lo16(zz.y), hi16(zz.y)}; float y[4];
; #pragma unroll
;                 for (int j = 0; j < 4; ++j) { const float xv = bf2f(*(const bf16_t*)(hb + S2_XT + xo + (8 * ig + j) * RS2)); y[j] = (acc[4 * ig + j] + Dsk * xv) * siluf_(zf[j]); ss += y[j] * y[j]; }
;                 u32x2 w; w.x = pk2(y[0], y[1]); w.y = pk2(y[2], y[3]);
;                 *(u32x2*)(P_yg + tok * 4096 + hd * 64 + p0) = w; }
.Lssd_wB_2:
	v_lshlrev_b32_e32 v56, 16, v168
	v_and_b32_e32 v57, 0xffff0000, v168
	v_mul_f32_e32 v55, 0xbfb8aa3b, v56
	v_mul_f32_e32 v58, 0xbfb8aa3b, v57
	v_exp_f32_e32 v55, v55
	v_exp_f32_e32 v58, v58
	global_store_dwordx2 v[32:33], v[52:53], off offset:16
	v_add_f32_e32 v34, v50, v34
	v_add_f32_e32 v52, 1.0, v55
	v_add_f32_e32 v53, 1.0, v58
	v_rcp_f32_e32 v52, v52
	v_rcp_f32_e32 v53, v53
	ds_read_u16 v58, v54 offset:55552
	ds_read_u16 v55, v54 offset:55696
	ds_read_u16 v60, v54 offset:55840
	ds_read_u16 v59, v54 offset:55984
	ds_read_u16 v61, v54 offset:56704
	ds_read_u16 v62, v54 offset:56848
	ds_read_u16 v63, v54 offset:56992
	ds_read_u16 v64, v54 offset:57136
	s_waitcnt lgkmcnt(6)
	v_lshlrev_b32_e32 v55, 16, v55
	v_lshlrev_b32_e32 v54, 16, v58
	v_pk_fma_f32 v[40:41], v[156:157], v[54:55], v[40:41]
	v_pk_mul_f32 v[52:53], v[52:53], v[56:57]
	s_waitcnt lgkmcnt(4)
	v_lshlrev_b32_e32 v59, 16, v59
	v_pk_mul_f32 v[40:41], v[52:53], v[40:41]
	v_lshlrev_b32_e32 v52, 16, v169
	v_and_b32_e32 v53, 0xffff0000, v169
	v_mul_f32_e32 v54, 0xbfb8aa3b, v52
	v_exp_f32_e32 v56, v54
	v_mul_f32_e32 v54, 0xbfb8aa3b, v53
	v_exp_f32_e32 v57, v54
	v_lshlrev_b32_e32 v58, 16, v60
	v_add_f32_e32 v56, 1.0, v56
	v_rcp_f32_e32 v56, v56
	v_add_f32_e32 v57, 1.0, v57
	v_rcp_f32_e32 v57, v57
	v_pk_fma_f32 v[42:43], v[156:157], v[58:59], v[42:43]
	v_pk_mul_f32 v[54:55], v[40:41], v[40:41]
	v_cvt_pk_bf16_f32 v40, v40, v41
	v_pk_mul_f32 v[52:53], v[56:57], v[52:53]
	v_add_f32_e32 v34, v34, v35
	v_pk_mul_f32 v[42:43], v[52:53], v[42:43]
	v_add_f32_e32 v34, v34, v36
	v_pk_mul_f32 v[52:53], v[42:43], v[42:43]
	v_cvt_pk_bf16_f32 v41, v42, v43
	s_cmp_eq_u32 s33, 31
	s_cbranch_scc1 .Lssd_wA_3
	s_waitcnt vmcnt(16)
	s_branch .Lssd_wB_3

; #define P_part   WSP(float, WS_PART)
; DI float bf2f(bf16_t u) { return __uint_as_float(((unsigned)u) << 16); }
; DI unsigned pk2(float lo, float hi) { f32x2 v = {lo, hi}; bf16x2_t b = __builtin_convertvector(v, bf16x2_t); return __builtin_bit_cast(unsigned, b); }
; DI float lo16(unsigned u) { return __uint_as_float(u << 16); }
; DI float hi16(unsigned u) { return __uint_as_float(u & 0xffff0000u); }
; DI float siluf_(float x) { return x * __builtin_amdgcn_rcpf(1.f + __expf(-x)); }
; DI void ssd_pair_item(const Params& P, unsigned char* smem, int b, int hp) {
;     ...
; #pragma unroll
;             for (int ig = 0; ig < 4; ++ig) { const int p0 = 32 * ph + 8 * ig + 4 * hh;
;                 const u32x2 zz = zr[ig];
;                 const float zf[4] = {lo16(zz.x), hi16(zz.x), lo16(zz.y), hi16(zz.y)}; float y[4];
; #pragma unroll
;                 for (int j = 0; j < 4; ++j) { const float xv = bf2f(*(const bf16_t*)(hb + S2_XT + xo + (8 * ig + j) * RS2)); y[j] = (acc[4 * ig + j] + Dsk * xv) * siluf_(zf[j]); ss += y[j] * y[j]; }
;                 u32x2 w; w.x = pk2(y[0], y[1]); w.y = pk2(y[2], y[3]);
;                 *(u32x2*)(P_yg + tok * 4096 + hd * 64 + p0) = w; }
;             ss += __shfl_xor(ss, 32);
;             if (hh == 0) P_part[tok * 64 + hd * 2 + ph] = ss;
.Lssd_wB_3:
	v_lshlrev_b32_e32 v42, 16, v170
	v_and_b32_e32 v43, 0xffff0000, v170
	v_mul_f32_e32 v56, 0xbfb8aa3b, v42
	v_mul_f32_e32 v57, 0xbfb8aa3b, v43
	v_exp_f32_e32 v56, v56
	v_exp_f32_e32 v57, v57
	global_store_dwordx2 v[32:33], v[40:41], off offset:32
	v_add_f32_e32 v34, v34, v37
	v_add_f32_e32 v40, 1.0, v56
	v_add_f32_e32 v41, 1.0, v57
	v_rcp_f32_e32 v40, v40
	v_rcp_f32_e32 v41, v41
	s_waitcnt lgkmcnt(2)
	v_lshlrev_b32_e32 v57, 16, v62
	v_lshlrev_b32_e32 v56, 16, v61
	v_pk_fma_f32 v[44:45], v[156:157], v[56:57], v[44:45]
	v_pk_mul_f32 v[40:41], v[40:41], v[42:43]
	v_lshlrev_b32_e32 v42, 16, v171
	v_pk_mul_f32 v[40:41], v[40:41], v[44:45]
	v_and_b32_e32 v43, 0xffff0000, v171
	v_mul_f32_e32 v44, 0xbfb8aa3b, v42
	v_exp_f32_e32 v56, v44
	v_mul_f32_e32 v44, 0xbfb8aa3b, v43
	v_exp_f32_e32 v57, v44
	v_add_f32_e32 v34, v34, v38
	v_add_f32_e32 v56, 1.0, v56
	v_rcp_f32_e32 v56, v56
	v_add_f32_e32 v57, 1.0, v57
	v_rcp_f32_e32 v57, v57
	v_add_f32_e32 v34, v34, v39
	v_add_f32_e32 v34, v34, v54
	v_add_f32_e32 v34, v34, v55
	s_waitcnt lgkmcnt(0)
	v_lshlrev_b32_e32 v59, 16, v64
	v_lshlrev_b32_e32 v58, 16, v63
	v_add_f32_e32 v34, v34, v52
	v_pk_mul_f32 v[44:45], v[40:41], v[40:41]
	v_pk_fma_f32 v[46:47], v[156:157], v[58:59], v[46:47]
	v_pk_mul_f32 v[42:43], v[56:57], v[42:43]
	v_add_f32_e32 v34, v34, v53
	v_and_b32_e32 v36, 64, v182
	v_pk_mul_f32 v[42:43], v[42:43], v[46:47]
	v_add_f32_e32 v34, v34, v44
	v_xor_b32_e32 v35, 32, v182
	v_add_u32_e32 v36, 64, v36
	v_pk_mul_f32 v[46:47], v[42:43], v[42:43]
	v_add_f32_e32 v34, v34, v45
	v_cmp_lt_i32_e32 vcc, v35, v36
	v_add_f32_e32 v34, v34, v46
	v_add_f32_e32 v34, v34, v47
	v_cndmask_b32_e32 v35, v182, v35, vcc
	v_lshlrev_b32_e32 v35, 2, v35
	ds_bpermute_b32 v35, v35, v34
	v_cvt_pk_bf16_f32 v36, v40, v41
	v_cvt_pk_bf16_f32 v37, v42, v43
	v_cmp_eq_u32_e32 vcc, 0, v200
	global_store_dwordx2 v[32:33], v[36:37], off offset:48
	s_and_saveexec_b64 s[2:3], vcc
	s_cbranch_execz .LBB0_318
	v_lshlrev_b64 v[32:33], 8, v[48:49]
	v_lshl_add_u64 v[32:33], v[164:165], 0, v[32:33]
	v_lshlrev_b32_e32 v64, 2, v199
	v_lshl_add_u64 v[32:33], v[32:33], 0, v[64:65]
	s_waitcnt lgkmcnt(0)
	v_add_f32_e32 v34, v34, v35
	global_store_dword v[32:33], v34, off
